# S7 epilogue: the second residual batch (8 bf16 loads) issued together with the first into spare registers; counted waits vmcnt(8)/vmcnt(16)
# speedup vs baseline: 1.0029x; 1.0029x over previous
.LBB0_1487:
	v_lshl_add_u32 v148, s35, 8, v152
	v_lshl_add_u32 v144, s36, 8, v154
	v_ashrrev_i32_e32 v145, 31, v144
	v_ashrrev_i32_e32 v149, 31, v148
	v_lshl_add_u64 v[146:147], v[144:145], 1, s[8:9]
	v_lshlrev_b64 v[150:151], 12, v[148:149]
	v_or_b32_e32 v182, 16, v148
	v_lshl_add_u64 v[150:151], v[146:147], 0, v[150:151]
	v_ashrrev_i32_e32 v183, 31, v182
	global_load_dwordx4 v[158:161], v[150:151], off
	global_load_dwordx4 v[162:165], v[150:151], off offset:256
	v_lshlrev_b64 v[150:151], 12, v[182:183]
	v_or_b32_e32 v190, 32, v148
	v_lshl_add_u64 v[150:151], v[146:147], 0, v[150:151]
	v_ashrrev_i32_e32 v191, 31, v190
	global_load_dwordx4 v[166:169], v[150:151], off
	global_load_dwordx4 v[170:173], v[150:151], off offset:256
	v_lshlrev_b64 v[150:151], 12, v[190:191]
	v_lshl_add_u64 v[178:179], v[146:147], 0, v[150:151]
	global_load_dwordx4 v[174:177], v[178:179], off
	v_or_b32_e32 v150, 48, v148
	global_load_dwordx4 v[178:181], v[178:179], off offset:256
	v_ashrrev_i32_e32 v151, 31, v150
	v_lshlrev_b64 v[186:187], 12, v[150:151]
	v_lshl_add_u64 v[144:145], v[144:145], 2, s[52:53]
	v_lshlrev_b64 v[184:185], 13, v[148:149]
	v_lshlrev_b64 v[182:183], 13, v[182:183]
	v_lshl_add_u64 v[186:187], v[146:147], 0, v[186:187]
	v_lshl_add_u64 v[192:193], v[144:145], 0, v[184:185]
	v_lshl_add_u64 v[194:195], v[144:145], 0, v[182:183]
	global_load_dwordx4 v[182:185], v[186:187], off
	s_nop 0
	global_load_dwordx4 v[186:189], v[186:187], off offset:256
	v_add_u32_e32 v210, 0x80, v148
	v_ashrrev_i32_e32 v211, 31, v210
	v_lshlrev_b64 v[208:209], 12, v[210:211]
	v_lshl_add_u64 v[208:209], v[146:147], 0, v[208:209]
	global_load_dwordx4 v[224:227], v[208:209], off
	global_load_dwordx4 v[228:231], v[208:209], off offset:256
	v_add_u32_e32 v210, 0x90, v148
	v_ashrrev_i32_e32 v211, 31, v210
	v_lshlrev_b64 v[208:209], 12, v[210:211]
	v_lshl_add_u64 v[208:209], v[146:147], 0, v[208:209]
	global_load_dwordx4 v[232:235], v[208:209], off
	global_load_dwordx4 v[236:239], v[208:209], off offset:256
	v_add_u32_e32 v210, 0xa0, v148
	v_ashrrev_i32_e32 v211, 31, v210
	v_lshlrev_b64 v[208:209], 12, v[210:211]
	v_lshl_add_u64 v[208:209], v[146:147], 0, v[208:209]
	global_load_dwordx4 v[240:243], v[208:209], off
	global_load_dwordx4 v[244:247], v[208:209], off offset:256
	v_add_u32_e32 v210, 0xb0, v148
	v_ashrrev_i32_e32 v211, 31, v210
	v_lshlrev_b64 v[208:209], 12, v[210:211]
	v_lshl_add_u64 v[208:209], v[146:147], 0, v[208:209]
	global_load_dwordx4 v[248:251], v[208:209], off
	global_load_dwordx4 v[204:207], v[208:209], off offset:256
	s_and_b64 vcc, exec, s[6:7]
	s_mov_b64 s[6:7], -1
	s_waitcnt vmcnt(8) lgkmcnt(0)
	v_lshlrev_b32_e32 v196, 16, v158
	v_and_b32_e32 v197, 0xffff0000, v158
	v_lshlrev_b32_e32 v158, 16, v159
	v_and_b32_e32 v159, 0xffff0000, v159
	v_lshlrev_b32_e32 v198, 16, v160
	v_and_b32_e32 v199, 0xffff0000, v160
	v_lshlrev_b32_e32 v160, 16, v161
	v_and_b32_e32 v161, 0xffff0000, v161
	v_lshlrev_b32_e32 v200, 16, v162
	v_and_b32_e32 v201, 0xffff0000, v162
	v_lshlrev_b32_e32 v162, 16, v163
	v_and_b32_e32 v163, 0xffff0000, v163
	v_lshlrev_b32_e32 v202, 16, v164
	v_and_b32_e32 v203, 0xffff0000, v164
	v_lshlrev_b32_e32 v164, 16, v165
	v_and_b32_e32 v165, 0xffff0000, v165
	v_pk_fma_f32 v[126:127], v[126:127], 0.5, v[158:159] op_sel_hi:[1,0,1]
	v_pk_fma_f32 v[122:123], v[122:123], 0.5, v[160:161] op_sel_hi:[1,0,1]
	v_pk_fma_f32 v[118:119], v[118:119], 0.5, v[162:163] op_sel_hi:[1,0,1]
	v_pk_fma_f32 v[114:115], v[114:115], 0.5, v[164:165] op_sel_hi:[1,0,1]
	v_lshlrev_b32_e32 v158, 16, v166
	v_and_b32_e32 v159, 0xffff0000, v166
	v_lshlrev_b32_e32 v160, 16, v167
	v_and_b32_e32 v161, 0xffff0000, v167
	v_lshlrev_b32_e32 v162, 16, v168
	v_and_b32_e32 v163, 0xffff0000, v168
	v_lshlrev_b32_e32 v164, 16, v169
	v_and_b32_e32 v165, 0xffff0000, v169
	v_lshlrev_b32_e32 v166, 16, v170
	v_and_b32_e32 v167, 0xffff0000, v170
	v_lshlrev_b32_e32 v168, 16, v171
	v_and_b32_e32 v169, 0xffff0000, v171
	v_lshlrev_b32_e32 v170, 16, v172
	v_and_b32_e32 v171, 0xffff0000, v172
	v_lshlrev_b32_e32 v172, 16, v173
	v_and_b32_e32 v173, 0xffff0000, v173
	v_pk_fma_f32 v[124:125], v[124:125], 0.5, v[196:197] op_sel_hi:[1,0,1]
	v_pk_fma_f32 v[110:111], v[110:111], 0.5, v[160:161] op_sel_hi:[1,0,1]
	v_pk_fma_f32 v[108:109], v[108:109], 0.5, v[158:159] op_sel_hi:[1,0,1]
	v_pk_fma_f32 v[104:105], v[104:105], 0.5, v[162:163] op_sel_hi:[1,0,1]
	v_pk_fma_f32 v[102:103], v[102:103], 0.5, v[168:169] op_sel_hi:[1,0,1]
	v_pk_fma_f32 v[100:101], v[100:101], 0.5, v[166:167] op_sel_hi:[1,0,1]
	v_pk_fma_f32 v[98:99], v[98:99], 0.5, v[172:173] op_sel_hi:[1,0,1]
	v_pk_fma_f32 v[96:97], v[96:97], 0.5, v[170:171] op_sel_hi:[1,0,1]
	v_pk_fma_f32 v[120:121], v[120:121], 0.5, v[198:199] op_sel_hi:[1,0,1]
	v_pk_fma_f32 v[116:117], v[116:117], 0.5, v[200:201] op_sel_hi:[1,0,1]
	v_pk_fma_f32 v[112:113], v[112:113], 0.5, v[202:203] op_sel_hi:[1,0,1]
	global_store_dwordx4 v[192:193], v[124:127], off
	global_store_dwordx4 v[192:193], v[120:123], off offset:16
	global_store_dwordx4 v[192:193], v[116:119], off offset:512
	global_store_dwordx4 v[192:193], v[112:115], off offset:528
	v_pk_fma_f32 v[106:107], v[106:107], 0.5, v[164:165] op_sel_hi:[1,0,1]
	global_store_dwordx4 v[194:195], v[108:111], off
	global_store_dwordx4 v[194:195], v[104:107], off offset:16
	global_store_dwordx4 v[194:195], v[100:103], off offset:512
	global_store_dwordx4 v[194:195], v[96:99], off offset:528
	v_lshlrev_b32_e32 v104, 16, v177
	v_lshlrev_b32_e32 v100, 16, v175
	v_lshlrev_b64 v[96:97], 13, v[190:191]
	v_lshlrev_b32_e32 v98, 16, v174
	v_and_b32_e32 v99, 0xffff0000, v174
	v_and_b32_e32 v101, 0xffff0000, v175
	v_lshlrev_b32_e32 v102, 16, v176
	v_and_b32_e32 v103, 0xffff0000, v176
	v_and_b32_e32 v105, 0xffff0000, v177
	v_lshl_add_u64 v[96:97], v[144:145], 0, v[96:97]
	v_pk_fma_f32 v[94:95], v[94:95], 0.5, v[100:101] op_sel_hi:[1,0,1]
	v_pk_fma_f32 v[92:93], v[92:93], 0.5, v[98:99] op_sel_hi:[1,0,1]
	v_pk_fma_f32 v[90:91], v[90:91], 0.5, v[104:105] op_sel_hi:[1,0,1]
	v_pk_fma_f32 v[88:89], v[88:89], 0.5, v[102:103] op_sel_hi:[1,0,1]
	global_store_dwordx4 v[96:97], v[92:95], off
	global_store_dwordx4 v[96:97], v[88:91], off offset:16
	v_add_u32_e32 v98, 0x90, v148
	v_lshlrev_b32_e32 v92, 16, v180
	v_lshlrev_b32_e32 v88, 16, v178
	v_and_b32_e32 v89, 0xffff0000, v178
	v_lshlrev_b32_e32 v90, 16, v179
	v_and_b32_e32 v91, 0xffff0000, v179
	v_and_b32_e32 v93, 0xffff0000, v180
	v_lshlrev_b32_e32 v94, 16, v181
	v_and_b32_e32 v95, 0xffff0000, v181
	v_pk_fma_f32 v[86:87], v[86:87], 0.5, v[90:91] op_sel_hi:[1,0,1]
	v_pk_fma_f32 v[84:85], v[84:85], 0.5, v[88:89] op_sel_hi:[1,0,1]
	v_pk_fma_f32 v[76:77], v[76:77], 0.5, v[92:93] op_sel_hi:[1,0,1]
	v_pk_fma_f32 v[78:79], v[78:79], 0.5, v[94:95] op_sel_hi:[1,0,1]
	global_store_dwordx4 v[96:97], v[84:87], off offset:512
	global_store_dwordx4 v[96:97], v[76:79], off offset:528
	v_lshlrev_b32_e32 v88, 16, v185
	v_lshlrev_b32_e32 v86, 16, v184
	v_lshlrev_b64 v[76:77], 13, v[150:151]
	v_lshl_add_u64 v[84:85], v[144:145], 0, v[76:77]
	v_lshlrev_b32_e32 v76, 16, v182
	v_and_b32_e32 v77, 0xffff0000, v182
	v_lshlrev_b32_e32 v78, 16, v183
	v_and_b32_e32 v79, 0xffff0000, v183
	v_and_b32_e32 v87, 0xffff0000, v184
	v_and_b32_e32 v89, 0xffff0000, v185
	v_pk_fma_f32 v[78:79], v[82:83], 0.5, v[78:79] op_sel_hi:[1,0,1]
	v_pk_fma_f32 v[76:77], v[80:81], 0.5, v[76:77] op_sel_hi:[1,0,1]
	v_pk_fma_f32 v[74:75], v[74:75], 0.5, v[88:89] op_sel_hi:[1,0,1]
	v_pk_fma_f32 v[72:73], v[72:73], 0.5, v[86:87] op_sel_hi:[1,0,1]
	global_store_dwordx4 v[84:85], v[76:79], off
	global_store_dwordx4 v[84:85], v[72:75], off offset:16
	v_add_u32_e32 v96, 0x80, v148
	v_lshlrev_b32_e32 v76, 16, v188
	v_lshlrev_b32_e32 v72, 16, v186
	v_and_b32_e32 v73, 0xffff0000, v186
	v_lshlrev_b32_e32 v74, 16, v187
	v_and_b32_e32 v75, 0xffff0000, v187
	v_and_b32_e32 v77, 0xffff0000, v188
	v_lshlrev_b32_e32 v78, 16, v189
	v_and_b32_e32 v79, 0xffff0000, v189
	v_pk_fma_f32 v[70:71], v[70:71], 0.5, v[74:75] op_sel_hi:[1,0,1]
	v_pk_fma_f32 v[68:69], v[68:69], 0.5, v[72:73] op_sel_hi:[1,0,1]
	v_pk_fma_f32 v[64:65], v[64:65], 0.5, v[76:77] op_sel_hi:[1,0,1]
	v_ashrrev_i32_e32 v97, 31, v96
	v_pk_fma_f32 v[66:67], v[66:67], 0.5, v[78:79] op_sel_hi:[1,0,1]
	global_store_dwordx4 v[84:85], v[68:71], off offset:512
	global_store_dwordx4 v[84:85], v[64:67], off offset:528
	v_ashrrev_i32_e32 v99, 31, v98
	v_add_u32_e32 v100, 0xa0, v148
	v_lshlrev_b64 v[64:65], 12, v[96:97]
	v_lshl_add_u64 v[64:65], v[146:147], 0, v[64:65]
	s_waitcnt vmcnt(16)
	v_mov_b64_e32 v[68:69], v[224:225]
	v_mov_b64_e32 v[70:71], v[226:227]
	v_mov_b64_e32 v[72:73], v[228:229]
	v_mov_b64_e32 v[74:75], v[230:231]
	v_lshlrev_b64 v[64:65], 12, v[98:99]
	v_lshl_add_u64 v[64:65], v[146:147], 0, v[64:65]
	v_mov_b64_e32 v[76:77], v[232:233]
	v_mov_b64_e32 v[78:79], v[234:235]
	v_mov_b64_e32 v[80:81], v[236:237]
	v_mov_b64_e32 v[82:83], v[238:239]
	v_ashrrev_i32_e32 v101, 31, v100
	v_lshlrev_b64 v[64:65], 12, v[100:101]
	v_lshl_add_u64 v[64:65], v[146:147], 0, v[64:65]
	v_mov_b64_e32 v[84:85], v[240:241]
	v_mov_b64_e32 v[86:87], v[242:243]
	v_mov_b64_e32 v[88:89], v[244:245]
	v_mov_b64_e32 v[90:91], v[246:247]
	v_add_u32_e32 v102, 0xb0, v148
	v_ashrrev_i32_e32 v103, 31, v102
	v_lshlrev_b64 v[64:65], 12, v[102:103]
	v_lshl_add_u64 v[64:65], v[146:147], 0, v[64:65]
	v_mov_b64_e32 v[92:93], v[248:249]
	v_mov_b64_e32 v[94:95], v[250:251]
	s_nop 0
	v_mov_b64_e32 v[64:65], v[204:205]
	v_mov_b64_e32 v[66:67], v[206:207]
	v_lshlrev_b64 v[96:97], 13, v[96:97]
	v_lshl_add_u64 v[96:97], v[144:145], 0, v[96:97]
	s_waitcnt lgkmcnt(0)
	v_lshlrev_b32_e32 v104, 16, v68
	v_and_b32_e32 v105, 0xffff0000, v68
	v_lshlrev_b32_e32 v68, 16, v69
	v_and_b32_e32 v69, 0xffff0000, v69
	v_lshlrev_b32_e32 v106, 16, v70
	v_and_b32_e32 v107, 0xffff0000, v70
	v_lshlrev_b32_e32 v70, 16, v71
	v_and_b32_e32 v71, 0xffff0000, v71
	v_pk_fma_f32 v[62:63], v[62:63], 0.5, v[68:69] op_sel_hi:[1,0,1]
	v_pk_fma_f32 v[60:61], v[60:61], 0.5, v[104:105] op_sel_hi:[1,0,1]
	v_pk_fma_f32 v[58:59], v[58:59], 0.5, v[70:71] op_sel_hi:[1,0,1]
	v_pk_fma_f32 v[56:57], v[56:57], 0.5, v[106:107] op_sel_hi:[1,0,1]
	global_store_dwordx4 v[96:97], v[60:63], off
	global_store_dwordx4 v[96:97], v[56:59], off offset:16
	s_nop 0
	v_lshlrev_b32_e32 v60, 16, v74
	v_lshlrev_b32_e32 v56, 16, v72
	v_and_b32_e32 v57, 0xffff0000, v72
	v_lshlrev_b32_e32 v58, 16, v73
	v_and_b32_e32 v59, 0xffff0000, v73
	v_and_b32_e32 v61, 0xffff0000, v74
	v_lshlrev_b32_e32 v62, 16, v75
	v_and_b32_e32 v63, 0xffff0000, v75
	v_pk_fma_f32 v[54:55], v[54:55], 0.5, v[58:59] op_sel_hi:[1,0,1]
	v_pk_fma_f32 v[52:53], v[52:53], 0.5, v[56:57] op_sel_hi:[1,0,1]
	v_pk_fma_f32 v[44:45], v[44:45], 0.5, v[60:61] op_sel_hi:[1,0,1]
	v_pk_fma_f32 v[46:47], v[46:47], 0.5, v[62:63] op_sel_hi:[1,0,1]
	global_store_dwordx4 v[96:97], v[52:55], off offset:512
	global_store_dwordx4 v[96:97], v[44:47], off offset:528
	v_lshlrev_b32_e32 v56, 16, v79
	v_lshlrev_b32_e32 v54, 16, v78
	v_lshlrev_b64 v[44:45], 13, v[98:99]
	v_lshl_add_u64 v[52:53], v[144:145], 0, v[44:45]
	v_lshlrev_b32_e32 v44, 16, v76
	v_and_b32_e32 v45, 0xffff0000, v76
	v_lshlrev_b32_e32 v46, 16, v77
	v_and_b32_e32 v47, 0xffff0000, v77
	v_and_b32_e32 v55, 0xffff0000, v78
	v_and_b32_e32 v57, 0xffff0000, v79
	v_pk_fma_f32 v[46:47], v[50:51], 0.5, v[46:47] op_sel_hi:[1,0,1]
	v_pk_fma_f32 v[44:45], v[48:49], 0.5, v[44:45] op_sel_hi:[1,0,1]
	v_pk_fma_f32 v[42:43], v[42:43], 0.5, v[56:57] op_sel_hi:[1,0,1]
	v_pk_fma_f32 v[40:41], v[40:41], 0.5, v[54:55] op_sel_hi:[1,0,1]
	global_store_dwordx4 v[52:53], v[44:47], off
	global_store_dwordx4 v[52:53], v[40:43], off offset:16
	s_nop 0
	v_lshlrev_b32_e32 v44, 16, v82
	v_lshlrev_b32_e32 v40, 16, v80
	v_and_b32_e32 v41, 0xffff0000, v80
	v_lshlrev_b32_e32 v42, 16, v81
	v_and_b32_e32 v43, 0xffff0000, v81
	v_and_b32_e32 v45, 0xffff0000, v82
	v_lshlrev_b32_e32 v46, 16, v83
	v_and_b32_e32 v47, 0xffff0000, v83
	v_pk_fma_f32 v[38:39], v[38:39], 0.5, v[42:43] op_sel_hi:[1,0,1]
	v_pk_fma_f32 v[36:37], v[36:37], 0.5, v[40:41] op_sel_hi:[1,0,1]
	v_pk_fma_f32 v[28:29], v[28:29], 0.5, v[44:45] op_sel_hi:[1,0,1]
	v_pk_fma_f32 v[30:31], v[30:31], 0.5, v[46:47] op_sel_hi:[1,0,1]
	global_store_dwordx4 v[52:53], v[36:39], off offset:512
	global_store_dwordx4 v[52:53], v[28:31], off offset:528
	v_lshlrev_b32_e32 v40, 16, v87
	v_lshlrev_b32_e32 v38, 16, v86
	v_lshlrev_b64 v[28:29], 13, v[100:101]
	v_lshl_add_u64 v[36:37], v[144:145], 0, v[28:29]
	v_lshlrev_b32_e32 v28, 16, v84
	v_and_b32_e32 v29, 0xffff0000, v84
	v_lshlrev_b32_e32 v30, 16, v85
	v_and_b32_e32 v31, 0xffff0000, v85
	v_and_b32_e32 v39, 0xffff0000, v86
	v_and_b32_e32 v41, 0xffff0000, v87
	v_pk_fma_f32 v[30:31], v[34:35], 0.5, v[30:31] op_sel_hi:[1,0,1]
	v_pk_fma_f32 v[28:29], v[32:33], 0.5, v[28:29] op_sel_hi:[1,0,1]
	v_pk_fma_f32 v[26:27], v[26:27], 0.5, v[40:41] op_sel_hi:[1,0,1]
	v_pk_fma_f32 v[24:25], v[24:25], 0.5, v[38:39] op_sel_hi:[1,0,1]
	global_store_dwordx4 v[36:37], v[28:31], off
	global_store_dwordx4 v[36:37], v[24:27], off offset:16
	s_nop 0
	v_lshlrev_b32_e32 v28, 16, v90
	v_lshlrev_b32_e32 v24, 16, v88
	v_and_b32_e32 v25, 0xffff0000, v88
	v_lshlrev_b32_e32 v26, 16, v89
	v_and_b32_e32 v27, 0xffff0000, v89
	v_and_b32_e32 v29, 0xffff0000, v90
	v_lshlrev_b32_e32 v30, 16, v91
	v_and_b32_e32 v31, 0xffff0000, v91
	v_pk_fma_f32 v[22:23], v[22:23], 0.5, v[26:27] op_sel_hi:[1,0,1]
	v_pk_fma_f32 v[20:21], v[20:21], 0.5, v[24:25] op_sel_hi:[1,0,1]
	v_pk_fma_f32 v[12:13], v[12:13], 0.5, v[28:29] op_sel_hi:[1,0,1]
	v_pk_fma_f32 v[14:15], v[14:15], 0.5, v[30:31] op_sel_hi:[1,0,1]
	global_store_dwordx4 v[36:37], v[20:23], off offset:512
	global_store_dwordx4 v[36:37], v[12:15], off offset:528
	v_lshlrev_b32_e32 v24, 16, v95
	v_lshlrev_b32_e32 v22, 16, v94
	v_lshlrev_b64 v[12:13], 13, v[102:103]
	v_lshl_add_u64 v[20:21], v[144:145], 0, v[12:13]
	v_lshlrev_b32_e32 v12, 16, v92
	v_and_b32_e32 v13, 0xffff0000, v92
	v_lshlrev_b32_e32 v14, 16, v93
	v_and_b32_e32 v15, 0xffff0000, v93
	v_and_b32_e32 v23, 0xffff0000, v94
	v_and_b32_e32 v25, 0xffff0000, v95
	v_pk_fma_f32 v[14:15], v[18:19], 0.5, v[14:15] op_sel_hi:[1,0,1]
	v_pk_fma_f32 v[12:13], v[16:17], 0.5, v[12:13] op_sel_hi:[1,0,1]
	v_pk_fma_f32 v[10:11], v[10:11], 0.5, v[24:25] op_sel_hi:[1,0,1]
	v_pk_fma_f32 v[8:9], v[8:9], 0.5, v[22:23] op_sel_hi:[1,0,1]
	global_store_dwordx4 v[20:21], v[12:15], off
	global_store_dwordx4 v[20:21], v[8:11], off offset:16
	s_nop 0
	v_lshlrev_b32_e32 v12, 16, v66
	v_lshlrev_b32_e32 v8, 16, v64
	v_and_b32_e32 v9, 0xffff0000, v64
	v_lshlrev_b32_e32 v10, 16, v65
	v_and_b32_e32 v11, 0xffff0000, v65
	v_and_b32_e32 v13, 0xffff0000, v66
	v_lshlrev_b32_e32 v14, 16, v67
	v_and_b32_e32 v15, 0xffff0000, v67
	v_pk_fma_f32 v[6:7], v[6:7], 0.5, v[10:11] op_sel_hi:[1,0,1]
	v_pk_fma_f32 v[4:5], v[4:5], 0.5, v[8:9] op_sel_hi:[1,0,1]
	v_pk_fma_f32 v[2:3], v[2:3], 0.5, v[14:15] op_sel_hi:[1,0,1]
	v_pk_fma_f32 v[0:1], v[0:1], 0.5, v[12:13] op_sel_hi:[1,0,1]
	global_store_dwordx4 v[20:21], v[4:7], off offset:512
	global_store_dwordx4 v[20:21], v[0:3], off offset:528
	s_cbranch_vccnz .LBB0_1472
	s_and_b64 vcc, exec, s[60:61]
	s_cbranch_vccnz .LBB0_1471
	s_barrier
	s_branch .LBB0_1471
